# attention running-max reduction via v_permlane16/32_swap instead of two ds_bpermute round trips
# baseline (speedup 1.0000x reference)
; __device__ void attn_phase(PP p, int layer) {
;     ...
; #pragma unroll
;             for (int h = 0; h < 2; ++h) {
;                 f32x4 s0 = (f32x4){0.f, 0.f, 0.f, 0.f}, s1 = (f32x4){0.f, 0.f, 0.f, 0.f};
;                 s0 = __builtin_amdgcn_mfma_f32_16x16x32_bf16(kf[h][0], qf0, s0, 0, 0, 0); s0 = __builtin_amdgcn_mfma_f32_16x16x32_bf16(kf[h][1], qf1, s0, 0, 0, 0);
;                 s1 = __builtin_amdgcn_mfma_f32_16x16x32_bf16(kf[h][2], qf0, s1, 0, 0, 0); s1 = __builtin_amdgcn_mfma_f32_16x16x32_bf16(kf[h][3], qf1, s1, 0, 0, 0);
; #pragma unroll
;                 for (int e = 0; e < 8; ++e) { float sv = ((e < 4) ? s0[e & 3] : s1[e & 3]) + sc[h * 8 + e];
;                     if (band) { const int kcol = cs + quad * 8 + e; const bool ok = (kcol >= start) && (kcol < start + 16); sv = ok ? sv : -1e30f; }
;                     sc[h * 8 + e] = sv; }
;             }
;             float mx = sc[0];
; #pragma unroll
;             for (int e = 1; e < 16; ++e) mx = fmaxf(mx, sc[e]);
;             mx = fmaxf(mx, __shfl_xor(mx, 16)); mx = fmaxf(mx, __shfl_xor(mx, 32));
;             const float mnew = fmaxf(mrun, mx), alpha = __expf(mrun - mnew);
;             float ps = 0.f, pv[16];
; #pragma unroll
;             for (int e = 0; e < 16; ++e) { pv[e] = __expf(sc[e] - mnew); ps += pv[e]; }
;             lrun = lrun * alpha + ps; mrun = mnew;
.LBB0_366:
	s_or_b64 exec, exec, s[24:25]
	s_waitcnt vmcnt(0)
	v_mfma_f32_16x16x32_bf16 v[60:63], v[60:63], v[16:19], 0
	s_add_i32 s40, s40, 2
	v_cmp_ge_u32_e32 vcc, s40, v148
	v_add_u32_e32 v150, 64, v150
	v_mfma_f32_16x16x32_bf16 v[64:67], v[64:67], v[16:19], 0
	v_add_u32_e32 v151, 0x80, v151
	s_or_b64 s[62:63], vcc, s[62:63]
	v_mfma_f32_16x16x32_bf16 v[56:59], v[56:59], v[20:23], v[60:63]
	v_mfma_f32_16x16x32_bf16 v[64:67], v[68:71], v[20:23], v[64:67]
	s_nop 6
	v_add_f32_e32 v56, v158, v56
	v_cndmask_b32_e64 v60, v205, v56, s[14:15]
	v_add_f32_e32 v64, v154, v64
	v_add_f32_e32 v65, v153, v65
	v_cndmask_b32_e64 v153, v56, v60, s[22:23]
	v_mfma_f32_16x16x32_bf16 v[60:63], v[80:83], v[16:19], 0
	v_cndmask_b32_e64 v68, v205, v64, s[6:7]
	v_add_f32_e32 v66, v156, v66
	v_cndmask_b32_e64 v69, v205, v65, s[8:9]
	v_cndmask_b32_e64 v68, v64, v68, s[22:23]
	v_add_f32_e32 v64, v155, v67
	v_add_f32_e32 v56, v157, v57
	v_cndmask_b32_e64 v70, v205, v66, s[10:11]
	v_cndmask_b32_e64 v69, v65, v69, s[22:23]
	v_cndmask_b32_e64 v65, v205, v64, s[12:13]
	v_cndmask_b32_e64 v57, v205, v56, s[16:17]
	v_cndmask_b32_e64 v70, v66, v70, s[22:23]
	v_cndmask_b32_e64 v71, v64, v65, s[22:23]
	v_cndmask_b32_e64 v80, v56, v57, s[22:23]
	v_mfma_f32_16x16x32_bf16 v[60:63], v[72:75], v[20:23], v[60:63]
	v_add_f32_e32 v56, v162, v58
	v_cndmask_b32_e64 v57, v205, v56, s[18:19]
	v_cndmask_b32_e64 v72, v56, v57, s[22:23]
	v_mfma_f32_16x16x32_bf16 v[64:67], v[84:87], v[16:19], 0
	v_add_f32_e32 v56, v159, v59
	v_cndmask_b32_e64 v57, v205, v56, s[20:21]
	v_cndmask_b32_e64 v73, v56, v57, s[22:23]
	v_mfma_f32_16x16x32_bf16 v[56:59], v[76:79], v[20:23], v[64:67]
	v_add_f32_e32 v60, v167, v60
	v_add_f32_e32 v61, v166, v61
	v_add_f32_e32 v62, v169, v62
	s_nop 0
	v_cndmask_b32_e64 v64, v205, v60, s[6:7]
	v_cndmask_b32_e64 v60, v60, v64, s[22:23]
	v_cndmask_b32_e64 v64, v205, v61, s[8:9]
	v_cndmask_b32_e64 v61, v61, v64, s[22:23]
	v_cndmask_b32_e64 v64, v205, v62, s[10:11]
	v_add_f32_e32 v63, v168, v63
	v_cndmask_b32_e64 v62, v62, v64, s[22:23]
	v_cndmask_b32_e64 v64, v205, v63, s[12:13]
	v_add_f32_e32 v56, v171, v56
	v_cndmask_b32_e64 v63, v63, v64, s[22:23]
	v_cndmask_b32_e64 v64, v205, v56, s[14:15]
	v_add_f32_e32 v57, v170, v57
	v_cndmask_b32_e64 v56, v56, v64, s[22:23]
	v_cndmask_b32_e64 v64, v205, v57, s[16:17]
	v_add_f32_e32 v58, v173, v58
	v_cndmask_b32_e64 v57, v57, v64, s[22:23]
	v_cndmask_b32_e64 v64, v205, v58, s[18:19]
	v_add_f32_e32 v59, v172, v59
	v_cndmask_b32_e64 v58, v58, v64, s[22:23]
	v_cndmask_b32_e64 v64, v205, v59, s[20:21]
	v_cndmask_b32_e64 v59, v59, v64, s[22:23]
	v_max_f32_e32 v64, v68, v69
	v_max3_f32 v64, v64, v70, v71
	v_max3_f32 v64, v64, v153, v80
	v_max3_f32 v64, v64, v72, v73
	v_max3_f32 v64, v64, v60, v61
	v_max3_f32 v64, v64, v62, v63
	v_max3_f32 v64, v64, v56, v57
	v_max3_f32 v64, v64, v58, v59
	v_mov_b32_e32 v65, v64
	s_mov_b64 s[22:23], 0xf8
	v_lshl_add_u64 v[106:107], v[106:107], 0, s[22:23]
	s_nop 0
	v_permlane16_swap_b32 v65, v64
	v_max_f32_e32 v64, v64, v65
	v_mov_b32_e32 v65, v64
	s_nop 1
	v_permlane32_swap_b32 v65, v64
	v_max3_f32 v64, v152, v64, v65
	v_sub_f32_e32 v60, v60, v64
	v_mul_f32_e32 v60, 0x3fb8aa3b, v60
	v_sub_f32_e32 v56, v56, v64
	v_sub_f32_e32 v65, v152, v64
	v_exp_f32_e32 v74, v60
	v_sub_f32_e32 v60, v61, v64
	v_mul_f32_e32 v56, 0x3fb8aa3b, v56
	v_mul_f32_e32 v65, 0x3fb8aa3b, v65
	v_sub_f32_e32 v66, v68, v64
	v_sub_f32_e32 v67, v69, v64
	v_sub_f32_e32 v68, v70, v64
	v_sub_f32_e32 v69, v71, v64
	v_sub_f32_e32 v70, v153, v64
	v_sub_f32_e32 v71, v80, v64
	v_sub_f32_e32 v72, v72, v64
	v_sub_f32_e32 v73, v73, v64
	v_mul_f32_e32 v60, 0x3fb8aa3b, v60
	v_exp_f32_e32 v78, v56
	v_sub_f32_e32 v56, v57, v64
	v_mul_f32_e32 v66, 0x3fb8aa3b, v66
	v_mul_f32_e32 v67, 0x3fb8aa3b, v67
	v_mul_f32_e32 v68, 0x3fb8aa3b, v68
	v_mul_f32_e32 v69, 0x3fb8aa3b, v69
	v_mul_f32_e32 v70, 0x3fb8aa3b, v70
	v_mul_f32_e32 v71, 0x3fb8aa3b, v71
	v_mul_f32_e32 v72, 0x3fb8aa3b, v72
	v_mul_f32_e32 v73, 0x3fb8aa3b, v73
	v_exp_f32_e32 v75, v60
	v_sub_f32_e32 v60, v62, v64
	v_mul_f32_e32 v56, 0x3fb8aa3b, v56
	v_exp_f32_e32 v65, v65
	v_exp_f32_e32 v66, v66
	v_exp_f32_e32 v67, v67
	v_exp_f32_e32 v68, v68
	v_exp_f32_e32 v69, v69
	v_exp_f32_e32 v70, v70
	v_exp_f32_e32 v71, v71
	v_exp_f32_e32 v72, v72
	v_exp_f32_e32 v73, v73
	v_mul_f32_e32 v60, 0x3fb8aa3b, v60
	v_exp_f32_e32 v79, v56
	v_sub_f32_e32 v56, v58, v64
	v_exp_f32_e32 v76, v60
	v_sub_f32_e32 v60, v63, v64
	v_mul_f32_e32 v56, 0x3fb8aa3b, v56
	v_mul_f32_e32 v60, 0x3fb8aa3b, v60
	v_exp_f32_e32 v80, v56
	v_sub_f32_e32 v56, v59, v64
	v_exp_f32_e32 v77, v60
	ds_bpermute_b32 v60, v140, v65
	ds_bpermute_b32 v62, v142, v65
	ds_bpermute_b32 v63, v143, v65
	ds_bpermute_b32 v61, v141, v65
	v_mul_f32_e32 v56, 0x3fb8aa3b, v56
	v_exp_f32_e32 v81, v56
	v_cvt_pk_bf16_f32 v56, v66, v67
	v_cvt_pk_bf16_f32 v57, v68, v69
	v_cvt_pk_bf16_f32 v58, v70, v71
	v_cvt_pk_bf16_f32 v59, v72, v73
	s_waitcnt lgkmcnt(1)
	v_pk_mul_f32 v[14:15], v[14:15], v[62:63]
	s_waitcnt lgkmcnt(0)
	v_pk_mul_f32 v[12:13], v[12:13], v[60:61]
	v_pk_mul_f32 v[10:11], v[10:11], v[62:63]
	v_pk_mul_f32 v[8:9], v[8:9], v[60:61]
	v_mfma_f32_16x16x32_bf16 v[12:15], v[56:59], v[28:31], v[12:15]
	v_add_f32_e32 v28, 0, v66
	v_pk_mul_f32 v[6:7], v[6:7], v[62:63]
	v_pk_mul_f32 v[4:5], v[4:5], v[60:61]
	v_mfma_f32_16x16x32_bf16 v[8:11], v[56:59], v[24:27], v[8:11]
	v_add_f32_e32 v24, v67, v28
	v_add_f32_e32 v24, v68, v24
	v_add_f32_e32 v24, v69, v24
	v_add_f32_e32 v24, v70, v24
	v_add_f32_e32 v24, v71, v24
	v_add_f32_e32 v24, v72, v24
	v_add_f32_e32 v24, v73, v24
	v_add_f32_e32 v24, v74, v24
	v_pk_mul_f32 v[2:3], v[2:3], v[62:63]
	v_pk_mul_f32 v[0:1], v[0:1], v[60:61]
	v_cvt_pk_bf16_f32 v26, v74, v75
	v_cvt_pk_bf16_f32 v27, v76, v77
	v_cvt_pk_bf16_f32 v28, v78, v79
	v_cvt_pk_bf16_f32 v29, v80, v81
	v_add_f32_e32 v24, v75, v24
	v_mfma_f32_16x16x32_bf16 v[4:7], v[56:59], v[36:39], v[4:7]
	v_add_f32_e32 v24, v76, v24
	v_add_f32_e32 v24, v77, v24
	v_add_f32_e32 v24, v78, v24
	v_mfma_f32_16x16x32_bf16 v[0:3], v[56:59], v[32:35], v[0:3]
	v_add_f32_e32 v24, v79, v24
	v_add_f32_e32 v24, v80, v24
	v_add_f32_e32 v24, v81, v24
	v_mfma_f32_16x16x32_bf16 v[12:15], v[26:29], v[44:47], v[12:15]
	v_fmac_f32_e32 v24, v147, v65
	v_mov_b32_e32 v152, v64
	v_mov_b32_e32 v147, v24
	v_mfma_f32_16x16x32_bf16 v[8:11], v[26:29], v[40:43], v[8:11]
	v_mfma_f32_16x16x32_bf16 v[4:7], v[26:29], v[52:55], v[4:7]
	v_mfma_f32_16x16x32_bf16 v[0:3], v[26:29], v[48:51], v[0:3]
	s_andn2_b64 exec, exec, s[62:63]
	s_cbranch_execz .LBB0_360
